# in-proj tile columns rotated per row-group so every workgroup gets one V-transpose tile, six gate tiles and one GLU tile (was 2/0 split)
# baseline (speedup 1.0000x reference)
.LBB0_315:
	s_or_b64 exec, exec, s[2:3]
	s_mov_b64 s[2:3], s[78:79]
	s_waitcnt lgkmcnt(0)
	s_barrier
	s_load_dwordx2 s[6:7], s[2:3], 0xf0
	s_mov_b32 s38, s97
	s_mov_b32 s39, s76
	v_mov_b32_e32 v1, v218
	s_cmpk_lt_i32 s38, 0xa00
	v_mov_b32_e32 v1, v218
	s_cselect_b64 s[2:3], -1, 0
	s_cmpk_gt_i32 s38, 0x9ff
	v_readfirstlane_b32 s18, v1
	s_cbranch_scc1 .LBB0_317
	s_ashr_i32 s4, s38, 31
	s_lshr_b32 s4, s4, 29
	s_add_i32 s4, s38, s4
	s_ashr_i32 s5, s4, 3
	s_and_b32 s4, s4, -8
	s_sub_i32 s4, s38, s4
	s_cmp_lt_i32 s4, 0
	s_movk_i32 s8, 0x141
	s_cselect_b32 s8, s8, 0x140
	s_mul_i32 s4, s4, s8
	s_add_i32 s4, s4, s5
	s_mul_hi_i32 s5, s4, 0x66666667
	s_lshr_b32 s8, s5, 31
	s_ashr_i32 s5, s5, 5
	s_add_i32 s5, s5, s8
	s_lshl_b32 s8, s5, 2
	s_mulk_i32 s5, 0x50
	s_sub_i32 s4, s4, s5
	s_bfe_i32 s5, s4, 0x80000
	s_bfe_u32 s5, s5, 0x2000d
	s_add_i32 s5, s4, s5
	s_bfe_i32 s9, s5, 0x80000
	s_and_b32 s5, s5, 0xfc
	s_sub_i32 s4, s4, s5
	s_sext_i32_i16 s9, s9
	s_sext_i32_i8 s4, s4
	s_add_i32 s4, s8, s4
	s_ashr_i32 s26, s9, 2
	s_bfe_u32 s5, s8, 0x20002
	s_mul_i32 s5, s5, 18
	s_add_i32 s26, s26, s5
	s_sub_i32 s5, s26, 40
	s_cmp_ge_i32 s26, 40
	s_cselect_b32 s26, s5, s26
	s_sub_i32 s5, s26, 20
	s_cmp_ge_i32 s26, 20
	s_cselect_b32 s26, s5, s26

.LBB0_323:
	s_add_i32 s69, s69, 1
	s_mul_i32 s2, s69, s65
	s_mul_hi_u32 s3, s69, s39
	s_add_i32 s3, s3, s2
	s_mul_i32 s2, s69, s39
	s_add_u32 s22, s2, s38
	s_addc_u32 s23, s3, s66
	v_mov_b64_e32 v[2:3], 0xa00
	v_cmp_lt_i64_e64 s[2:3], s[22:23], v[2:3]
	v_mov_b64_e32 v[2:3], 0x9ff
	v_cmp_gt_i64_e32 vcc, s[22:23], v[2:3]
	s_cbranch_vccnz .LBB0_325
	s_ashr_i32 s5, s22, 31
	s_lshr_b32 s5, s5, 29
	s_add_i32 s5, s22, s5
	s_ashr_i32 s18, s5, 3
	s_and_b32 s5, s5, -8
	s_sub_i32 s5, s22, s5
	s_cmp_lt_i32 s5, 0
	s_cselect_b32 s19, s1, 0x140
	s_mul_i32 s5, s5, s19
	s_add_i32 s5, s5, s18
	s_mul_hi_i32 s18, s5, 0x66666667
	s_lshr_b32 s19, s18, 31
	s_ashr_i32 s18, s18, 5
	s_add_i32 s18, s18, s19
	s_lshl_b32 s19, s18, 2
	s_sub_i32 s20, 0x80, s19
	s_min_i32 s20, s20, 4
	s_abs_i32 s21, s20
	v_cvt_f32_u32_e32 v2, s21
	s_sub_i32 s23, 0, s21
	s_mulk_i32 s18, 0x50
	s_sub_i32 s5, s5, s18
	v_rcp_iflag_f32_e32 v2, v2
	s_abs_i32 s18, s5
	s_xor_b32 s22, s5, s20
	s_ashr_i32 s22, s22, 31
	v_mul_f32_e32 v2, 0x4f7ffffe, v2
	v_cvt_u32_f32_e32 v2, v2
	s_nop 0
	v_readfirstlane_b32 s24, v2
	s_mul_i32 s23, s23, s24
	s_mul_hi_u32 s23, s24, s23
	s_add_i32 s24, s24, s23
	s_mul_hi_u32 s23, s18, s24
	s_mul_i32 s24, s23, s21
	s_sub_i32 s18, s18, s24
	s_add_i32 s25, s23, 1
	s_sub_i32 s24, s18, s21
	s_cmp_ge_u32 s18, s21
	s_cselect_b32 s23, s25, s23
	s_cselect_b32 s18, s24, s18
	s_add_i32 s24, s23, 1
	s_cmp_ge_u32 s18, s21
	s_cselect_b32 s18, s24, s23
	s_xor_b32 s18, s18, s22
	s_sub_i32 s18, s18, s22
	s_mul_i32 s20, s18, s20
	s_sub_i32 s5, s5, s20
	s_add_i32 s20, s19, s5
	s_bfe_u32 s22, s19, 0x20002
	s_mul_i32 s22, s22, 18
	s_add_i32 s18, s18, s22
	s_sub_i32 s22, s18, 40
	s_cmp_ge_i32 s18, 40
	s_cselect_b32 s18, s22, s18
	s_sub_i32 s22, s18, 20
	s_cmp_ge_i32 s18, 20
	s_cselect_b32 s18, s22, s18
